# v29 + phase_final row loop: final_g loaded once, next row prefetched before the reduction, one wait per row
# baseline (speedup 1.0000x reference)
.LBB0_1770:
	v_readlane_b32 s0, v183, 0
	s_lshl_b32 s0, s0, 2
	v_ashrrev_i32_e32 v2, 6, v104
	v_add_u32_e32 v4, s0, v2
	s_mov_b32 s1, 0x8000
	v_cmp_gt_i32_e32 vcc, s1, v4
	s_and_saveexec_b64 s[2:3], vcc
	v_readlane_b32 s20, v181, 54
	v_readlane_b32 s21, v181, 55
	s_cbranch_execz .LBB0_1773
	v_and_b32_e32 v0, 64, v110
	v_add_u32_e32 v0, 64, v0
	v_xor_b32_e32 v1, 32, v110
	v_cmp_lt_i32_e32 vcc, v1, v0
	v_readlane_b32 s4, v182, 3
	v_ashrrev_i32_e32 v3, 31, v2
	v_cndmask_b32_e32 v1, v110, v1, vcc
	v_lshlrev_b32_e32 v5, 2, v1
	v_xor_b32_e32 v1, 16, v110
	v_cmp_lt_i32_e32 vcc, v1, v0
	s_ashr_i32 s1, s0, 31
	v_readlane_b32 s5, v182, 4
	v_cndmask_b32_e32 v1, v110, v1, vcc
	v_lshlrev_b32_e32 v6, 2, v1
	v_xor_b32_e32 v1, 8, v110
	v_cmp_lt_i32_e32 vcc, v1, v0
	v_readlane_b32 s6, v182, 5
	v_readlane_b32 s7, v182, 6
	v_cndmask_b32_e32 v1, v110, v1, vcc
	v_lshlrev_b32_e32 v7, 2, v1
	v_xor_b32_e32 v1, 4, v110
	v_cmp_lt_i32_e32 vcc, v1, v0
	v_readlane_b32 s8, v182, 7
	v_readlane_b32 s9, v182, 8
	v_cndmask_b32_e32 v1, v110, v1, vcc
	v_lshlrev_b32_e32 v8, 2, v1
	v_xor_b32_e32 v1, 2, v110
	v_cmp_lt_i32_e32 vcc, v1, v0
	v_readlane_b32 s10, v182, 9
	v_readlane_b32 s11, v182, 10
	v_cndmask_b32_e32 v1, v110, v1, vcc
	v_lshlrev_b32_e32 v9, 2, v1
	v_xor_b32_e32 v1, 1, v110
	v_cmp_lt_i32_e32 vcc, v1, v0
	v_readlane_b32 s12, v182, 11
	v_readlane_b32 s13, v182, 12
	v_cndmask_b32_e32 v0, v110, v1, vcc
	v_readlane_b32 s14, v182, 13
	v_readlane_b32 s15, v182, 14
	v_lshl_add_u64 v[2:3], v[2:3], 0, s[0:1]
	v_lshlrev_b32_e32 v10, 2, v0
	v_lshlrev_b32_e32 v0, 4, v104
	v_lshlrev_b64 v[2:3], 12, v[2:3]
	v_and_b32_e32 v11, 63, v104
	v_readlane_b32 s0, v183, 1
	v_and_b32_e32 v0, 0x3f0, v0
	v_mov_b32_e32 v1, 0
	v_readlane_b32 s18, v182, 17
	v_readlane_b32 s19, v182, 18
	v_lshl_or_b32 v2, v11, 4, v2
	v_readlane_b32 s1, v183, 2
	v_readlane_b32 s2, v183, 3
	v_readlane_b32 s3, v183, 4
	v_readlane_b32 s12, v183, 13
	v_readlane_b32 s13, v183, 14
	v_lshl_add_u64 v[0:1], s[18:19], 0, v[0:1]
	s_mov_b64 s[0:1], 0
	v_lshl_add_u64 v[2:3], s[12:13], 0, v[2:3]
	v_mov_b32_e32 v11, 0x358637bd
	s_mov_b32 s2, 0x800000
	s_movk_i32 s3, 0x7fff
	v_readlane_b32 s16, v182, 15
	v_readlane_b32 s17, v182, 16
	v_readlane_b32 s4, v183, 5
	v_readlane_b32 s5, v183, 6
	v_readlane_b32 s6, v183, 7
	v_readlane_b32 s7, v183, 8
	v_readlane_b32 s8, v183, 9
	v_readlane_b32 s9, v183, 10
	v_readlane_b32 s10, v183, 11
	v_readlane_b32 s11, v183, 12
	v_readlane_b32 s14, v183, 15
	v_readlane_b32 s15, v183, 16
	global_load_dwordx4 v[48:51], v[0:1], off
	global_load_dwordx4 v[52:55], v[0:1], off offset:1024
	global_load_dwordx4 v[56:59], v[0:1], off offset:2048
	global_load_dwordx4 v[60:63], v[0:1], off offset:3072
	global_load_dwordx4 v[76:79], v[2:3], off
	global_load_dwordx4 v[80:83], v[2:3], off offset:1024
	global_load_dwordx4 v[84:87], v[2:3], off offset:2048
	global_load_dwordx4 v[88:91], v[2:3], off offset:3072
.LBB0_1772:
	v_add_u32_e32 v4, s50, v4
	v_lshl_add_u64 v[72:73], v[2:3], 0, s[20:21]
	v_cmp_lt_i32_e32 vcc, s3, v4
	s_or_b64 s[0:1], vcc, s[0:1]
	s_waitcnt vmcnt(0)
	v_mov_b32_e32 v12, v76
	v_mov_b32_e32 v13, v77
	v_mov_b32_e32 v14, v78
	v_mov_b32_e32 v15, v79
	v_mov_b32_e32 v16, v80
	v_mov_b32_e32 v17, v81
	v_mov_b32_e32 v18, v82
	v_mov_b32_e32 v19, v83
	v_mov_b32_e32 v20, v84
	v_mov_b32_e32 v21, v85
	v_mov_b32_e32 v22, v86
	v_mov_b32_e32 v23, v87
	v_mov_b32_e32 v24, v88
	v_mov_b32_e32 v25, v89
	v_mov_b32_e32 v26, v90
	v_mov_b32_e32 v27, v91
	s_cbranch_vccnz .Lfinal_nopf
	global_load_dwordx4 v[76:79], v[72:73], off
	global_load_dwordx4 v[80:83], v[72:73], off offset:1024
	global_load_dwordx4 v[84:87], v[72:73], off offset:2048
	global_load_dwordx4 v[88:91], v[72:73], off offset:3072
.Lfinal_nopf:
	v_mov_b32_e32 v34, v13
	v_mov_b32_e32 v35, v17
	v_mov_b32_e32 v32, v12
	v_mov_b32_e32 v33, v16
	v_mov_b32_e32 v42, v21
	v_mov_b32_e32 v43, v25
	v_pk_mul_f32 v[34:35], v[34:35], v[34:35]
	v_mov_b32_e32 v36, v14
	v_mov_b32_e32 v37, v18
	v_mov_b32_e32 v40, v20
	v_mov_b32_e32 v41, v24
	v_pk_mul_f32 v[42:43], v[42:43], v[42:43]
	v_pk_fma_f32 v[32:33], v[32:33], v[32:33], v[34:35]
	v_mov_b32_e32 v38, v15
	v_mov_b32_e32 v39, v19
	v_mov_b32_e32 v44, v22
	v_mov_b32_e32 v45, v26
	v_pk_fma_f32 v[34:35], v[40:41], v[40:41], v[42:43]
	v_pk_fma_f32 v[32:33], v[36:37], v[36:37], v[32:33]
	v_mov_b32_e32 v46, v23
	v_mov_b32_e32 v47, v27
	v_pk_fma_f32 v[34:35], v[44:45], v[44:45], v[34:35]
	v_pk_fma_f32 v[32:33], v[38:39], v[38:39], v[32:33]
	v_pk_fma_f32 v[34:35], v[46:47], v[46:47], v[34:35]
	v_add_f32_e32 v32, v32, v33
	v_add_f32_e32 v32, v32, v34
	v_add_f32_e32 v32, v32, v35
	ds_bpermute_b32 v33, v5, v32
	s_waitcnt lgkmcnt(0)
	v_add_f32_e32 v32, v32, v33
	ds_bpermute_b32 v33, v6, v32
	s_waitcnt lgkmcnt(0)
	v_add_f32_e32 v32, v32, v33
	ds_bpermute_b32 v33, v7, v32
	s_waitcnt lgkmcnt(0)
	v_add_f32_e32 v32, v32, v33
	ds_bpermute_b32 v33, v8, v32
	s_waitcnt lgkmcnt(0)
	v_add_f32_e32 v32, v32, v33
	ds_bpermute_b32 v33, v9, v32
	s_waitcnt lgkmcnt(0)
	v_add_f32_e32 v32, v32, v33
	ds_bpermute_b32 v33, v10, v32
	s_waitcnt lgkmcnt(0)
	v_add_f32_e32 v32, v32, v33
	v_fmamk_f32 v32, v32, 0x3a800000, v11
	v_mul_f32_e32 v33, 0x4b800000, v32
	v_cmp_gt_f32_e32 vcc, s2, v32
	s_nop 1
	v_cndmask_b32_e32 v32, v32, v33, vcc
	v_rsq_f32_e32 v32, v32
	s_nop 0
	v_mul_f32_e32 v33, 0x45800000, v32
	v_cndmask_b32_e32 v32, v32, v33, vcc
	v_pk_mul_f32 v[12:13], v[12:13], v[32:33] op_sel_hi:[1,0]
	v_pk_mul_f32 v[14:15], v[14:15], v[32:33] op_sel_hi:[1,0]
	v_pk_mul_f32 v[16:17], v[16:17], v[32:33] op_sel_hi:[1,0]
	v_pk_mul_f32 v[18:19], v[18:19], v[32:33] op_sel_hi:[1,0]
	v_pk_mul_f32 v[20:21], v[20:21], v[32:33] op_sel_hi:[1,0]
	v_pk_mul_f32 v[22:23], v[22:23], v[32:33] op_sel_hi:[1,0]
	v_pk_mul_f32 v[24:25], v[24:25], v[32:33] op_sel_hi:[1,0]
	v_pk_mul_f32 v[26:27], v[26:27], v[32:33] op_sel_hi:[1,0]
	v_pk_mul_f32 v[12:13], v[48:49], v[12:13]
	v_pk_mul_f32 v[14:15], v[50:51], v[14:15]
	v_pk_mul_f32 v[16:17], v[52:53], v[16:17]
	v_pk_mul_f32 v[18:19], v[54:55], v[18:19]
	v_pk_mul_f32 v[20:21], v[20:21], v[56:57]
	v_pk_mul_f32 v[22:23], v[22:23], v[58:59]
	v_pk_mul_f32 v[24:25], v[24:25], v[60:61]
	v_pk_mul_f32 v[26:27], v[26:27], v[62:63]
	global_store_dwordx4 v[2:3], v[12:15], off
	global_store_dwordx4 v[2:3], v[16:19], off offset:1024
	global_store_dwordx4 v[2:3], v[20:23], off offset:2048
	global_store_dwordx4 v[2:3], v[24:27], off offset:3072
	v_mov_b32_e32 v2, v72
	v_mov_b32_e32 v3, v73
	s_andn2_b64 exec, exec, s[0:1]
	s_cbranch_execnz .LBB0_1772
